# NSA flash loops: max3 chain; selected branch drops the causal test for key blocks entirely below the wave's rows
# baseline (speedup 1.0000x reference)
.LBB0_1395:
	s_mul_i32 s9, s43, 0x4800
	v_add_u32_e32 v111, s9, v108
	v_add_u32_e32 v110, v111, v91
	ds_read_b128 v[32:35], v110 offset:37376
	ds_read_b128 v[36:39], v110 offset:32768
	ds_read_b128 v[112:115], v110 offset:32800
	ds_read_b128 v[116:119], v110 offset:37408
	s_xor_b64 s[0:1], s[0:1], -1
	s_andn2_b64 vcc, exec, s[0:1]
	s_waitcnt lgkmcnt(2)
	v_mfma_f32_32x32x16_f16 v[48:63], v[36:39], v[64:67], 0
	s_mov_b64 s[0:1], s[50:51]
	v_mfma_f32_32x32x16_f16 v[32:47], v[32:35], v[64:67], 0
	s_waitcnt lgkmcnt(1)
	v_mfma_f32_32x32x16_f16 v[48:63], v[112:115], v[68:71], v[48:63]
	s_waitcnt lgkmcnt(0)
	v_mfma_f32_32x32x16_f16 v[32:47], v[116:119], v[68:71], v[32:47]
	ds_read_b128 v[112:115], v110 offset:32832
	ds_read_b128 v[116:119], v110 offset:37440
	s_waitcnt lgkmcnt(1)
	v_mfma_f32_32x32x16_f16 v[48:63], v[112:115], v[72:75], v[48:63]
	s_waitcnt lgkmcnt(0)
	v_mfma_f32_32x32x16_f16 v[32:47], v[116:119], v[72:75], v[32:47]
	ds_read_b128 v[112:115], v110 offset:32864
	ds_read_b128 v[116:119], v110 offset:37472
	v_lshrrev_b32_e32 v110, s0, v106
	s_waitcnt lgkmcnt(1)
	v_mfma_f32_32x32x16_f16 v[48:63], v[112:115], v[76:79], v[48:63]
	v_and_b32_e32 v112, 1, v110
	v_or_b32_e32 v110, s8, v97
	s_waitcnt lgkmcnt(0)
	v_mfma_f32_32x32x16_f16 v[32:47], v[116:119], v[76:79], v[32:47]
	s_cbranch_vccnz .LBB0_1397
	v_cmp_eq_u32_e32 vcc, 1, v112
	s_or_b32 s0, s8, 63
	s_cmp_gt_i32 s0, s78
	s_cbranch_scc1 .Lsel_ma_slow
	s_nop 3
	v_cndmask_b32_e32 v48, v193, v48, vcc
	v_cndmask_b32_e32 v49, v193, v49, vcc
	v_cndmask_b32_e32 v50, v193, v50, vcc
	v_cndmask_b32_e32 v51, v193, v51, vcc
	v_cndmask_b32_e32 v52, v193, v52, vcc
	v_cndmask_b32_e32 v53, v193, v53, vcc
	v_cndmask_b32_e32 v54, v193, v54, vcc
	v_cndmask_b32_e32 v55, v193, v55, vcc
	v_cndmask_b32_e32 v56, v193, v56, vcc
	v_cndmask_b32_e32 v57, v193, v57, vcc
	v_cndmask_b32_e32 v58, v193, v58, vcc
	v_cndmask_b32_e32 v59, v193, v59, vcc
	v_cndmask_b32_e32 v60, v193, v60, vcc
	v_cndmask_b32_e32 v61, v193, v61, vcc
	v_cndmask_b32_e32 v62, v193, v62, vcc
	v_cndmask_b32_e32 v63, v193, v63, vcc
	s_branch .LBB0_1397
.Lsel_ma_slow:
	v_cmp_le_i32_e64 s[0:1], v110, v127
	s_and_b64 s[0:1], vcc, s[0:1]
	v_or_b32_e32 v113, 2, v110
	s_nop 2
	v_cndmask_b32_e64 v48, v193, v48, s[0:1]
	v_cmp_lt_i32_e64 s[0:1], v110, v127
	s_and_b64 s[0:1], vcc, s[0:1]
	s_nop 0
	v_cndmask_b32_e64 v49, v193, v49, s[0:1]
	v_cmp_le_i32_e64 s[0:1], v113, v127
	s_and_b64 s[0:1], vcc, s[0:1]
	v_or_b32_e32 v113, 3, v110
	v_cndmask_b32_e64 v50, v193, v50, s[0:1]
	v_cmp_le_i32_e64 s[0:1], v113, v127
	s_and_b64 s[0:1], vcc, s[0:1]
	v_or_b32_e32 v113, 8, v110
	v_cndmask_b32_e64 v51, v193, v51, s[0:1]
	v_cmp_le_i32_e64 s[0:1], v113, v127
	s_and_b64 s[0:1], vcc, s[0:1]
	v_or_b32_e32 v113, 9, v110
	v_cndmask_b32_e64 v52, v193, v52, s[0:1]
	v_cmp_le_i32_e64 s[0:1], v113, v127
	s_and_b64 s[0:1], vcc, s[0:1]
	v_or_b32_e32 v113, 10, v110
	v_cndmask_b32_e64 v53, v193, v53, s[0:1]
	v_cmp_le_i32_e64 s[0:1], v113, v127
	s_and_b64 s[0:1], vcc, s[0:1]
	v_or_b32_e32 v113, 11, v110
	v_cndmask_b32_e64 v54, v193, v54, s[0:1]
	v_cmp_le_i32_e64 s[0:1], v113, v127
	s_and_b64 s[0:1], vcc, s[0:1]
	v_or_b32_e32 v113, 16, v110
	v_cndmask_b32_e64 v55, v193, v55, s[0:1]
	v_cmp_le_i32_e64 s[0:1], v113, v127
	s_and_b64 s[0:1], vcc, s[0:1]
	v_or_b32_e32 v113, 17, v110
	v_cndmask_b32_e64 v56, v193, v56, s[0:1]
	v_cmp_le_i32_e64 s[0:1], v113, v127
	s_and_b64 s[0:1], vcc, s[0:1]
	v_or_b32_e32 v113, 18, v110
	v_cndmask_b32_e64 v57, v193, v57, s[0:1]
	v_cmp_le_i32_e64 s[0:1], v113, v127
	s_and_b64 s[0:1], vcc, s[0:1]
	v_or_b32_e32 v113, 19, v110
	v_cndmask_b32_e64 v58, v193, v58, s[0:1]
	v_cmp_le_i32_e64 s[0:1], v113, v127
	s_and_b64 s[0:1], vcc, s[0:1]
	v_or_b32_e32 v113, 24, v110
	v_cndmask_b32_e64 v59, v193, v59, s[0:1]
	v_cmp_le_i32_e64 s[0:1], v113, v127
	s_and_b64 s[0:1], vcc, s[0:1]
	v_or_b32_e32 v113, 25, v110
	v_cndmask_b32_e64 v60, v193, v60, s[0:1]
	v_cmp_le_i32_e64 s[0:1], v113, v127
	s_and_b64 s[0:1], vcc, s[0:1]
	v_or_b32_e32 v113, 26, v110
	v_cndmask_b32_e64 v61, v193, v61, s[0:1]
	v_cmp_le_i32_e64 s[0:1], v113, v127
	s_and_b64 s[0:1], vcc, s[0:1]
	v_or_b32_e32 v113, 27, v110
	v_cndmask_b32_e64 v62, v193, v62, s[0:1]
	v_cmp_le_i32_e64 s[0:1], v113, v127
	s_and_b64 vcc, vcc, s[0:1]
	v_cndmask_b32_e32 v63, v193, v63, vcc
.LBB0_1397:
	s_xor_b64 s[0:1], s[4:5], -1
	s_andn2_b64 vcc, exec, s[0:1]
	s_cbranch_vccnz .LBB0_1399
	v_cmp_eq_u32_e32 vcc, 1, v112
	s_or_b32 s0, s8, 63
	s_cmp_gt_i32 s0, s78
	s_cbranch_scc1 .Lsel_mb_slow
	s_nop 3
	v_cndmask_b32_e32 v32, v193, v32, vcc
	v_cndmask_b32_e32 v33, v193, v33, vcc
	v_cndmask_b32_e32 v34, v193, v34, vcc
	v_cndmask_b32_e32 v35, v193, v35, vcc
	v_cndmask_b32_e32 v36, v193, v36, vcc
	v_cndmask_b32_e32 v37, v193, v37, vcc
	v_cndmask_b32_e32 v38, v193, v38, vcc
	v_cndmask_b32_e32 v39, v193, v39, vcc
	v_cndmask_b32_e32 v40, v193, v40, vcc
	v_cndmask_b32_e32 v41, v193, v41, vcc
	v_cndmask_b32_e32 v42, v193, v42, vcc
	v_cndmask_b32_e32 v43, v193, v43, vcc
	v_cndmask_b32_e32 v44, v193, v44, vcc
	v_cndmask_b32_e32 v45, v193, v45, vcc
	v_cndmask_b32_e32 v46, v193, v46, vcc
	v_cndmask_b32_e32 v47, v193, v47, vcc
	s_branch .LBB0_1399
.Lsel_mb_slow:
	v_or_b32_e32 v112, 32, v110
	v_cmp_le_i32_e64 s[0:1], v112, v127
	s_and_b64 s[0:1], vcc, s[0:1]
	s_nop 3
	v_cndmask_b32_e64 v32, v193, v32, s[0:1]
	v_cmp_lt_i32_e64 s[0:1], v112, v127
	s_and_b64 s[0:1], vcc, s[0:1]
	v_or_b32_e32 v112, 34, v110
	v_cndmask_b32_e64 v33, v193, v33, s[0:1]
	v_cmp_le_i32_e64 s[0:1], v112, v127
	s_and_b64 s[0:1], vcc, s[0:1]
	v_or_b32_e32 v112, 35, v110
	v_cndmask_b32_e64 v34, v193, v34, s[0:1]
	v_cmp_le_i32_e64 s[0:1], v112, v127
	s_and_b64 s[0:1], vcc, s[0:1]
	v_or_b32_e32 v112, 40, v110
	v_cndmask_b32_e64 v35, v193, v35, s[0:1]
	v_cmp_le_i32_e64 s[0:1], v112, v127
	s_and_b64 s[0:1], vcc, s[0:1]
	v_or_b32_e32 v112, 41, v110
	v_cndmask_b32_e64 v36, v193, v36, s[0:1]
	v_cmp_le_i32_e64 s[0:1], v112, v127
	s_and_b64 s[0:1], vcc, s[0:1]
	v_or_b32_e32 v112, 42, v110
	v_cndmask_b32_e64 v37, v193, v37, s[0:1]
	v_cmp_le_i32_e64 s[0:1], v112, v127
	s_and_b64 s[0:1], vcc, s[0:1]
	v_or_b32_e32 v112, 43, v110
	v_cndmask_b32_e64 v38, v193, v38, s[0:1]
	v_cmp_le_i32_e64 s[0:1], v112, v127
	s_and_b64 s[0:1], vcc, s[0:1]
	v_or_b32_e32 v112, 48, v110
	v_cndmask_b32_e64 v39, v193, v39, s[0:1]
	v_cmp_le_i32_e64 s[0:1], v112, v127
	s_and_b64 s[0:1], vcc, s[0:1]
	v_or_b32_e32 v112, 49, v110
	v_cndmask_b32_e64 v40, v193, v40, s[0:1]
	v_cmp_le_i32_e64 s[0:1], v112, v127
	s_and_b64 s[0:1], vcc, s[0:1]
	v_or_b32_e32 v112, 50, v110
	v_cndmask_b32_e64 v41, v193, v41, s[0:1]
	v_cmp_le_i32_e64 s[0:1], v112, v127
	s_and_b64 s[0:1], vcc, s[0:1]
	v_or_b32_e32 v112, 51, v110
	v_cndmask_b32_e64 v42, v193, v42, s[0:1]
	v_cmp_le_i32_e64 s[0:1], v112, v127
	s_and_b64 s[0:1], vcc, s[0:1]
	v_or_b32_e32 v112, 56, v110
	v_cndmask_b32_e64 v43, v193, v43, s[0:1]
	v_cmp_le_i32_e64 s[0:1], v112, v127
	s_and_b64 s[0:1], vcc, s[0:1]
	v_or_b32_e32 v112, 57, v110
	v_cndmask_b32_e64 v44, v193, v44, s[0:1]
	v_cmp_le_i32_e64 s[0:1], v112, v127
	s_and_b64 s[0:1], vcc, s[0:1]
	v_or_b32_e32 v112, 58, v110
	v_cndmask_b32_e64 v45, v193, v45, s[0:1]
	v_cmp_le_i32_e64 s[0:1], v112, v127
	s_and_b64 s[0:1], vcc, s[0:1]
	v_or_b32_e32 v110, 59, v110
	v_cndmask_b32_e64 v46, v193, v46, s[0:1]
	v_cmp_le_i32_e64 s[0:1], v110, v127
	s_and_b64 vcc, vcc, s[0:1]
	v_cndmask_b32_e32 v47, v193, v47, vcc
.LBB0_1399:
	s_nop 7
	s_mov_b32 s0, 0xf149f2ca
	v_max3_f32 v110, v48, v32, s0
	v_max3_f32 v110, v110, v49, v33
	v_max3_f32 v110, v110, v50, v34
	v_max3_f32 v110, v110, v51, v35
	v_max3_f32 v110, v110, v52, v36
	v_max3_f32 v110, v110, v53, v37
	v_max3_f32 v110, v110, v54, v38
	v_max3_f32 v110, v110, v55, v39
	v_max3_f32 v110, v110, v56, v40
	v_max3_f32 v110, v110, v57, v41
	v_max3_f32 v110, v110, v58, v42
	v_max3_f32 v110, v110, v59, v43
	v_max3_f32 v110, v110, v60, v44
	v_max3_f32 v110, v110, v61, v45
	v_max3_f32 v110, v110, v62, v46
	v_max3_f32 v110, v110, v63, v47
	v_mov_b32_e32 v112, v192
	s_nop 0
	v_lshlrev_b32_e32 v112, 2, v112
	v_xor_b32_e32 v112, 0x80, v112
	ds_bpermute_b32 v112, v112, v110
	s_waitcnt lgkmcnt(0)
	v_max3_f32 v110, v102, v110, v112
	v_sub_f32_e32 v102, v102, v110
	v_exp_f32_e32 v102, v102
	s_nop 0
	v_cmp_neq_f32_e32 vcc, 1.0, v102
	s_cbranch_vccz .LBB0_1401
	v_pk_mul_f32 v[30:31], v[30:31], v[102:103] op_sel_hi:[1,0]
	v_pk_mul_f32 v[28:29], v[28:29], v[102:103] op_sel_hi:[1,0]
	v_pk_mul_f32 v[26:27], v[26:27], v[102:103] op_sel_hi:[1,0]
	v_pk_mul_f32 v[24:25], v[24:25], v[102:103] op_sel_hi:[1,0]
	v_pk_mul_f32 v[22:23], v[22:23], v[102:103] op_sel_hi:[1,0]
	v_pk_mul_f32 v[20:21], v[20:21], v[102:103] op_sel_hi:[1,0]
	v_pk_mul_f32 v[18:19], v[18:19], v[102:103] op_sel_hi:[1,0]
	v_pk_mul_f32 v[16:17], v[16:17], v[102:103] op_sel_hi:[1,0]
	v_pk_mul_f32 v[14:15], v[14:15], v[102:103] op_sel_hi:[1,0]
	v_pk_mul_f32 v[12:13], v[12:13], v[102:103] op_sel_hi:[1,0]
	v_pk_mul_f32 v[10:11], v[10:11], v[102:103] op_sel_hi:[1,0]
	v_pk_mul_f32 v[8:9], v[8:9], v[102:103] op_sel_hi:[1,0]
	v_pk_mul_f32 v[6:7], v[6:7], v[102:103] op_sel_hi:[1,0]
	v_pk_mul_f32 v[4:5], v[4:5], v[102:103] op_sel_hi:[1,0]
	v_pk_mul_f32 v[2:3], v[2:3], v[102:103] op_sel_hi:[1,0]
	v_pk_mul_f32 v[0:1], v[0:1], v[102:103] op_sel_hi:[1,0]

.LBB0_1430:
	s_nop 2
	s_mov_b32 s0, 0xf149f2ca
	v_max3_f32 v101, v48, v32, s0
	v_max3_f32 v101, v101, v49, v33
	v_max3_f32 v101, v101, v50, v34
	v_max3_f32 v101, v101, v51, v35
	v_max3_f32 v101, v101, v52, v36
	v_max3_f32 v101, v101, v53, v37
	v_max3_f32 v101, v101, v54, v38
	v_max3_f32 v101, v101, v55, v39
	v_max3_f32 v101, v101, v56, v40
	v_max3_f32 v101, v101, v57, v41
	v_max3_f32 v101, v101, v58, v42
	v_max3_f32 v101, v101, v59, v43
	v_max3_f32 v101, v101, v60, v44
	v_max3_f32 v101, v101, v61, v45
	v_max3_f32 v101, v101, v62, v46
	v_max3_f32 v101, v101, v63, v47
	v_mov_b32_e32 v105, v192
	s_nop 0
	v_lshlrev_b32_e32 v105, 2, v105
	v_xor_b32_e32 v105, 0x80, v105
	ds_bpermute_b32 v105, v105, v101
	s_waitcnt lgkmcnt(0)
	v_max3_f32 v101, v92, v101, v105
	v_sub_f32_e32 v92, v92, v101
	v_exp_f32_e32 v92, v92
	s_nop 0
	v_cmp_neq_f32_e32 vcc, 1.0, v92
	s_cbranch_vccz .LBB0_1432
	v_pk_mul_f32 v[30:31], v[30:31], v[92:93] op_sel_hi:[1,0]
	v_pk_mul_f32 v[28:29], v[28:29], v[92:93] op_sel_hi:[1,0]
	v_pk_mul_f32 v[26:27], v[26:27], v[92:93] op_sel_hi:[1,0]
	v_pk_mul_f32 v[24:25], v[24:25], v[92:93] op_sel_hi:[1,0]
	v_pk_mul_f32 v[22:23], v[22:23], v[92:93] op_sel_hi:[1,0]
	v_pk_mul_f32 v[20:21], v[20:21], v[92:93] op_sel_hi:[1,0]
	v_pk_mul_f32 v[18:19], v[18:19], v[92:93] op_sel_hi:[1,0]
	v_pk_mul_f32 v[16:17], v[16:17], v[92:93] op_sel_hi:[1,0]
	v_pk_mul_f32 v[14:15], v[14:15], v[92:93] op_sel_hi:[1,0]
	v_pk_mul_f32 v[12:13], v[12:13], v[92:93] op_sel_hi:[1,0]
	v_pk_mul_f32 v[10:11], v[10:11], v[92:93] op_sel_hi:[1,0]
	v_pk_mul_f32 v[8:9], v[8:9], v[92:93] op_sel_hi:[1,0]
	v_pk_mul_f32 v[6:7], v[6:7], v[92:93] op_sel_hi:[1,0]
	v_pk_mul_f32 v[4:5], v[4:5], v[92:93] op_sel_hi:[1,0]
	v_pk_mul_f32 v[2:3], v[2:3], v[92:93] op_sel_hi:[1,0]
	v_pk_mul_f32 v[0:1], v[0:1], v[92:93] op_sel_hi:[1,0]
